# norm phase split-K fold: 67 of the 72 serialized loads hoisted above the previous load's wait (two in flight), destinations redirected to v[248:251] where the old one is still being read
# speedup vs baseline: 1.0054x; 1.0054x over previous
.LBB0_92:
	v_ashrrev_i32_e32 v33, 31, v32
	v_lshlrev_b64 v[32:33], 13, v[32:33]
	v_lshl_add_u64 v[32:33], s[12:13], 0, v[32:33]
	v_lshl_add_u64 v[34:35], v[32:33], 0, v[174:175]
	global_load_dwordx4 v[96:99], v[192:193], off
	global_load_dwordx4 v[60:63], v[190:191], off
	global_load_dwordx4 v[112:115], v[34:35], off
	global_load_dwordx4 v[104:107], v[34:35], off offset:1024
	global_load_dwordx4 v[88:91], v[196:197], off
	global_load_dwordx4 v[56:59], v[194:195], off
	global_load_dwordx4 v[80:83], v[200:201], off
	global_load_dwordx4 v[52:55], v[198:199], off
	global_load_dwordx4 v[108:111], v[34:35], off offset:2048
	global_load_dwordx4 v[100:103], v[34:35], off offset:3072
	global_load_dwordx4 v[76:79], v[204:205], off
	global_load_dwordx4 v[48:51], v[202:203], off
	v_mov_b32_e32 v165, v175
	v_mov_b32_e32 v167, v175
	v_lshl_add_u64 v[34:35], v[32:33], 0, v[164:165]
	v_lshl_add_u64 v[36:37], v[32:33], 0, v[166:167]
	v_mov_b32_e32 v169, v175
	v_mov_b32_e32 v171, v175
	global_load_dwordx4 v[72:75], v[208:209], off
	global_load_dwordx4 v[44:47], v[206:207], off
	global_load_dwordx4 v[120:123], v[34:35], off
	global_load_dwordx4 v[116:119], v[36:37], off
	global_load_dwordx4 v[68:71], v[212:213], off
	s_nop 0
	global_load_dwordx4 v[36:39], v[210:211], off
	v_lshl_add_u64 v[34:35], v[32:33], 0, v[168:169]
	v_lshl_add_u64 v[32:33], v[32:33], 0, v[170:171]
	global_load_dwordx4 v[128:131], v[34:35], off
	global_load_dwordx4 v[124:127], v[32:33], off
	global_load_dwordx4 v[84:87], v[216:217], off
	global_load_dwordx4 v[40:43], v[214:215], off
	global_load_dwordx4 v[64:67], v[220:221], off
	s_nop 0
	global_load_dwordx4 v[32:35], v[218:219], off
	s_and_b64 vcc, exec, s[24:25]
	s_cbranch_vccz .LBB0_94
	v_ashrrev_i32_e32 v235, 31, v234
	v_lshlrev_b64 v[92:93], 13, v[234:235]
	v_lshl_add_u64 v[156:157], s[8:9], 0, v[92:93]
	v_lshl_add_u64 v[144:145], v[156:157], 0, v[174:175]
	global_load_dwordx4 v[92:95], v[144:145], off
	v_add_co_u32_e32 v142, vcc, 0x800000, v144
	s_mov_b32 s1, 0x801000
	s_nop 0
	v_addc_co_u32_e32 v143, vcc, 0, v145, vcc
	v_add_co_u32_e32 v148, vcc, 0x1000000, v144
	s_nop 1
	v_addc_co_u32_e32 v149, vcc, 0, v145, vcc
	v_add_co_u32_e32 v152, vcc, 0x1800000, v144
	global_load_dwordx4 v[248:251], v[142:143], off
	s_waitcnt vmcnt(1)
	v_pk_add_f32 v[132:133], v[94:95], 0 op_sel_hi:[1,0]
	v_pk_add_f32 v[134:135], v[92:93], 0 op_sel_hi:[1,0]
	v_addc_co_u32_e32 v153, vcc, 0, v145, vcc
	v_add_co_u32_e32 v154, vcc, 0x2000000, v144
	global_load_dwordx4 v[92:95], v[148:149], off
	s_waitcnt vmcnt(1)
	v_pk_add_f32 v[132:133], v[132:133], v[250:251]
	v_pk_add_f32 v[134:135], v[134:135], v[248:249]
	v_addc_co_u32_e32 v155, vcc, 0, v145, vcc
	v_add_co_u32_e32 v150, vcc, 0x2800000, v144
	global_load_dwordx4 v[248:251], v[152:153], off
	s_waitcnt vmcnt(1)
	v_pk_add_f32 v[132:133], v[132:133], v[94:95]
	v_pk_add_f32 v[134:135], v[134:135], v[92:93]
	v_addc_co_u32_e32 v151, vcc, 0, v145, vcc
	v_add_co_u32_e32 v146, vcc, 0x3000000, v144
	global_load_dwordx4 v[92:95], v[154:155], off
	s_waitcnt vmcnt(1)
	v_pk_add_f32 v[132:133], v[132:133], v[250:251]
	v_pk_add_f32 v[134:135], v[134:135], v[248:249]
	v_addc_co_u32_e32 v147, vcc, 0, v145, vcc
	v_add_co_u32_e32 v140, vcc, 0x3800000, v144
	global_load_dwordx4 v[248:251], v[150:151], off
	s_waitcnt vmcnt(1)
	v_pk_add_f32 v[132:133], v[132:133], v[94:95]
	v_pk_add_f32 v[134:135], v[134:135], v[92:93]
	v_addc_co_u32_e32 v141, vcc, 0, v145, vcc
	global_load_dwordx4 v[92:95], v[146:147], off
	s_waitcnt vmcnt(1)
	v_pk_add_f32 v[132:133], v[132:133], v[250:251]
	v_pk_add_f32 v[134:135], v[134:135], v[248:249]
	global_load_dwordx4 v[248:251], v[140:141], off
	s_waitcnt vmcnt(1)
	v_pk_add_f32 v[132:133], v[132:133], v[94:95]
	v_pk_add_f32 v[134:135], v[134:135], v[92:93]
	global_load_dwordx4 v[92:95], v[222:223], off
	s_waitcnt vmcnt(1)
	v_pk_add_f32 v[132:133], v[132:133], v[250:251]
	v_pk_add_f32 v[134:135], v[134:135], v[248:249]
	global_load_dwordx4 v[248:251], v[144:145], off offset:1024
	s_waitcnt vmcnt(1)
	v_pk_fma_f32 v[94:95], v[132:133], v[94:95], v[114:115]
	v_pk_fma_f32 v[92:93], v[134:135], v[92:93], v[112:113]
	global_load_dwordx4 v[132:135], v[142:143], off offset:1024
	s_waitcnt vmcnt(1)
	v_pk_add_f32 v[136:137], v[250:251], 0 op_sel_hi:[1,0]
	v_pk_add_f32 v[138:139], v[248:249], 0 op_sel_hi:[1,0]
	global_load_dwordx4 v[248:251], v[148:149], off offset:1024
	s_waitcnt vmcnt(1)
	v_pk_add_f32 v[136:137], v[136:137], v[134:135]
	v_pk_add_f32 v[138:139], v[138:139], v[132:133]
	global_load_dwordx4 v[132:135], v[152:153], off offset:1024
	s_waitcnt vmcnt(1)
	v_pk_add_f32 v[136:137], v[136:137], v[250:251]
	v_pk_add_f32 v[138:139], v[138:139], v[248:249]
	global_load_dwordx4 v[248:251], v[154:155], off offset:1024
	s_waitcnt vmcnt(1)
	v_pk_add_f32 v[136:137], v[136:137], v[134:135]
	v_pk_add_f32 v[138:139], v[138:139], v[132:133]
	global_load_dwordx4 v[132:135], v[150:151], off offset:1024
	s_waitcnt vmcnt(1)
	v_pk_add_f32 v[136:137], v[136:137], v[250:251]
	v_pk_add_f32 v[138:139], v[138:139], v[248:249]
	global_load_dwordx4 v[248:251], v[146:147], off offset:1024
	s_waitcnt vmcnt(1)
	v_pk_add_f32 v[136:137], v[136:137], v[134:135]
	v_pk_add_f32 v[138:139], v[138:139], v[132:133]
	global_load_dwordx4 v[132:135], v[140:141], off offset:1024
	s_waitcnt vmcnt(1)
	v_pk_add_f32 v[136:137], v[136:137], v[250:251]
	v_pk_add_f32 v[138:139], v[138:139], v[248:249]
	global_load_dwordx4 v[248:251], v[224:225], off
	s_waitcnt vmcnt(1)
	v_pk_add_f32 v[136:137], v[136:137], v[134:135]
	v_pk_add_f32 v[138:139], v[138:139], v[132:133]
	s_waitcnt vmcnt(0)
	v_pk_fma_f32 v[134:135], v[136:137], v[250:251], v[106:107]
	v_pk_fma_f32 v[132:133], v[138:139], v[248:249], v[104:105]
	global_load_dwordx4 v[136:139], v[144:145], off offset:2048
	global_load_dwordx4 v[248:251], v[142:143], off offset:2048
	s_waitcnt vmcnt(1)
	v_pk_add_f32 v[158:159], v[138:139], 0 op_sel_hi:[1,0]
	v_pk_add_f32 v[160:161], v[136:137], 0 op_sel_hi:[1,0]
	global_load_dwordx4 v[136:139], v[148:149], off offset:2048
	s_waitcnt vmcnt(1)
	v_pk_add_f32 v[158:159], v[158:159], v[250:251]
	v_pk_add_f32 v[160:161], v[160:161], v[248:249]
	global_load_dwordx4 v[248:251], v[152:153], off offset:2048
	s_waitcnt vmcnt(1)
	v_pk_add_f32 v[158:159], v[158:159], v[138:139]
	v_pk_add_f32 v[160:161], v[160:161], v[136:137]
	global_load_dwordx4 v[136:139], v[154:155], off offset:2048
	s_waitcnt vmcnt(1)
	v_pk_add_f32 v[158:159], v[158:159], v[250:251]
	v_pk_add_f32 v[160:161], v[160:161], v[248:249]
	global_load_dwordx4 v[248:251], v[150:151], off offset:2048
	s_waitcnt vmcnt(1)
	v_pk_add_f32 v[158:159], v[158:159], v[138:139]
	v_pk_add_f32 v[160:161], v[160:161], v[136:137]
	global_load_dwordx4 v[136:139], v[146:147], off offset:2048
	s_waitcnt vmcnt(1)
	v_pk_add_f32 v[158:159], v[158:159], v[250:251]
	v_pk_add_f32 v[160:161], v[160:161], v[248:249]
	global_load_dwordx4 v[248:251], v[140:141], off offset:2048
	s_waitcnt vmcnt(1)
	v_pk_add_f32 v[158:159], v[158:159], v[138:139]
	v_pk_add_f32 v[160:161], v[160:161], v[136:137]
	global_load_dwordx4 v[136:139], v[226:227], off
	s_waitcnt vmcnt(1)
	v_pk_add_f32 v[158:159], v[158:159], v[250:251]
	v_pk_add_f32 v[160:161], v[160:161], v[248:249]
	global_load_dwordx4 v[248:251], v[144:145], off offset:3072
	s_waitcnt vmcnt(1)
	v_pk_fma_f32 v[138:139], v[158:159], v[138:139], v[110:111]
	v_pk_fma_f32 v[136:137], v[160:161], v[136:137], v[108:109]
	global_load_dwordx4 v[158:161], v[142:143], off offset:3072
	s_waitcnt vmcnt(1)
	v_pk_add_f32 v[162:163], v[250:251], 0 op_sel_hi:[1,0]
	v_pk_add_f32 v[180:181], v[248:249], 0 op_sel_hi:[1,0]
	global_load_dwordx4 v[248:251], v[148:149], off offset:3072
	s_waitcnt vmcnt(1)
	v_pk_add_f32 v[142:143], v[162:163], v[160:161]
	v_pk_add_f32 v[162:163], v[180:181], v[158:159]
	global_load_dwordx4 v[158:161], v[152:153], off offset:3072
	s_waitcnt vmcnt(1)
	v_pk_add_f32 v[142:143], v[142:143], v[250:251]
	v_pk_add_f32 v[148:149], v[162:163], v[248:249]
	global_load_dwordx4 v[152:155], v[154:155], off offset:3072
	s_waitcnt vmcnt(1)
	v_pk_add_f32 v[148:149], v[148:149], v[158:159]
	v_pk_add_f32 v[142:143], v[142:143], v[160:161]
	v_add_co_u32_e32 v158, vcc, s1, v144
	s_mov_b32 s1, 0x1001000
	s_nop 0
	v_addc_co_u32_e32 v159, vcc, 0, v145, vcc
	v_add_co_u32_e32 v160, vcc, s1, v144
	s_mov_b32 s1, 0x1801000
	s_nop 0
	v_addc_co_u32_e32 v161, vcc, 0, v145, vcc
	v_add_co_u32_e32 v162, vcc, s1, v144
	s_mov_b32 s1, 0x2001000
	s_nop 0
	v_addc_co_u32_e32 v163, vcc, 0, v145, vcc
	v_add_co_u32_e32 v236, vcc, s1, v144
	s_mov_b32 s1, 0x2801000
	s_nop 0
	v_addc_co_u32_e32 v237, vcc, 0, v145, vcc
	v_add_co_u32_e32 v238, vcc, s1, v144
	s_mov_b32 s1, 0x3001000
	s_nop 0
	v_addc_co_u32_e32 v239, vcc, 0, v145, vcc
	v_add_co_u32_e32 v240, vcc, s1, v144
	s_mov_b32 s1, 0x3801000
	s_nop 0
	v_addc_co_u32_e32 v241, vcc, 0, v145, vcc
	v_add_co_u32_e32 v242, vcc, s1, v144
	s_movk_i32 s1, 0xf000
	s_nop 0
	v_addc_co_u32_e32 v243, vcc, 0, v145, vcc
	global_load_dwordx4 v[248:251], v[150:151], off offset:3072
	s_waitcnt vmcnt(1)
	v_pk_add_f32 v[152:153], v[148:149], v[152:153]
	v_pk_add_f32 v[142:143], v[142:143], v[154:155]
	global_load_dwordx4 v[146:149], v[146:147], off offset:3072
	s_waitcnt vmcnt(1)
	v_pk_add_f32 v[142:143], v[142:143], v[250:251]
	v_pk_add_f32 v[150:151], v[152:153], v[248:249]
	global_load_dwordx4 v[248:251], v[140:141], off offset:3072
	s_waitcnt vmcnt(1)
	v_pk_add_f32 v[148:149], v[142:143], v[148:149]
	v_pk_add_f32 v[146:147], v[150:151], v[146:147]
	global_load_dwordx4 v[140:143], v[228:229], off
	s_waitcnt vmcnt(1)
	v_pk_add_f32 v[148:149], v[148:149], v[250:251]
	v_pk_add_f32 v[146:147], v[146:147], v[248:249]
	s_waitcnt vmcnt(0)
	v_pk_fma_f32 v[140:141], v[146:147], v[140:141], v[100:101]
	v_lshl_add_u64 v[146:147], v[156:157], 0, v[164:165]
	v_pk_fma_f32 v[142:143], v[148:149], v[142:143], v[102:103]
	global_load_dwordx4 v[146:149], v[146:147], off
	global_load_dwordx4 v[248:251], v[158:159], off
	s_waitcnt vmcnt(1)
	v_pk_add_f32 v[150:151], v[148:149], 0 op_sel_hi:[1,0]
	v_pk_add_f32 v[152:153], v[146:147], 0 op_sel_hi:[1,0]
	global_load_dwordx4 v[146:149], v[160:161], off
	s_waitcnt vmcnt(1)
	v_pk_add_f32 v[150:151], v[150:151], v[250:251]
	v_pk_add_f32 v[152:153], v[152:153], v[248:249]
	global_load_dwordx4 v[248:251], v[162:163], off
	s_waitcnt vmcnt(1)
	v_pk_add_f32 v[150:151], v[150:151], v[148:149]
	v_pk_add_f32 v[152:153], v[152:153], v[146:147]
	global_load_dwordx4 v[146:149], v[236:237], off
	s_waitcnt vmcnt(1)
	v_pk_add_f32 v[150:151], v[150:151], v[250:251]
	v_pk_add_f32 v[152:153], v[152:153], v[248:249]
	global_load_dwordx4 v[248:251], v[238:239], off
	s_waitcnt vmcnt(1)
	v_pk_add_f32 v[150:151], v[150:151], v[148:149]
	v_pk_add_f32 v[152:153], v[152:153], v[146:147]
	global_load_dwordx4 v[146:149], v[240:241], off
	s_waitcnt vmcnt(1)
	v_pk_add_f32 v[150:151], v[150:151], v[250:251]
	v_pk_add_f32 v[152:153], v[152:153], v[248:249]
	global_load_dwordx4 v[248:251], v[242:243], off
	s_waitcnt vmcnt(1)
	v_pk_add_f32 v[148:149], v[150:151], v[148:149]
	v_pk_add_f32 v[150:151], v[152:153], v[146:147]
	global_load_dwordx4 v[144:147], v[230:231], off offset:-4096
	s_waitcnt vmcnt(1)
	v_pk_add_f32 v[148:149], v[148:149], v[250:251]
	v_pk_add_f32 v[150:151], v[150:151], v[248:249]
	s_waitcnt vmcnt(0)
	v_pk_fma_f32 v[146:147], v[148:149], v[146:147], v[122:123]
	v_lshl_add_u64 v[148:149], v[156:157], 0, v[166:167]
	v_pk_fma_f32 v[144:145], v[150:151], v[144:145], v[120:121]
	global_load_dwordx4 v[148:151], v[148:149], off
	global_load_dwordx4 v[248:251], v[158:159], off offset:1024
	s_waitcnt vmcnt(1)
	v_pk_add_f32 v[152:153], v[150:151], 0 op_sel_hi:[1,0]
	v_pk_add_f32 v[154:155], v[148:149], 0 op_sel_hi:[1,0]
	global_load_dwordx4 v[148:151], v[160:161], off offset:1024
	s_waitcnt vmcnt(1)
	v_pk_add_f32 v[152:153], v[152:153], v[250:251]
	v_pk_add_f32 v[154:155], v[154:155], v[248:249]
	global_load_dwordx4 v[248:251], v[162:163], off offset:1024
	s_waitcnt vmcnt(1)
	v_pk_add_f32 v[152:153], v[152:153], v[150:151]
	v_pk_add_f32 v[154:155], v[154:155], v[148:149]
	global_load_dwordx4 v[148:151], v[236:237], off offset:1024
	s_waitcnt vmcnt(1)
	v_pk_add_f32 v[152:153], v[152:153], v[250:251]
	v_pk_add_f32 v[154:155], v[154:155], v[248:249]
	global_load_dwordx4 v[248:251], v[238:239], off offset:1024
	s_waitcnt vmcnt(1)
	v_pk_add_f32 v[152:153], v[152:153], v[150:151]
	v_pk_add_f32 v[154:155], v[154:155], v[148:149]
	global_load_dwordx4 v[148:151], v[240:241], off offset:1024
	s_waitcnt vmcnt(1)
	v_pk_add_f32 v[152:153], v[152:153], v[250:251]
	v_pk_add_f32 v[154:155], v[154:155], v[248:249]
	global_load_dwordx4 v[248:251], v[242:243], off offset:1024
	s_waitcnt vmcnt(1)
	v_pk_add_f32 v[152:153], v[152:153], v[150:151]
	v_pk_add_f32 v[154:155], v[154:155], v[148:149]
	global_load_dwordx4 v[148:151], v[230:231], off offset:-3072
	s_waitcnt vmcnt(1)
	v_pk_add_f32 v[152:153], v[152:153], v[250:251]
	v_pk_add_f32 v[154:155], v[154:155], v[248:249]
	s_waitcnt vmcnt(0)
	v_pk_fma_f32 v[150:151], v[152:153], v[150:151], v[118:119]
	v_lshl_add_u64 v[152:153], v[156:157], 0, v[168:169]
	v_pk_fma_f32 v[148:149], v[154:155], v[148:149], v[116:117]
	global_load_dwordx4 v[152:155], v[152:153], off
	v_lshl_add_u64 v[156:157], v[156:157], 0, v[170:171]
	global_load_dwordx4 v[248:251], v[158:159], off offset:2048
	s_waitcnt vmcnt(1)
	v_pk_add_f32 v[180:181], v[154:155], 0 op_sel_hi:[1,0]
	v_pk_add_f32 v[182:183], v[152:153], 0 op_sel_hi:[1,0]
	global_load_dwordx4 v[152:155], v[160:161], off offset:2048
	s_waitcnt vmcnt(1)
	v_pk_add_f32 v[180:181], v[180:181], v[250:251]
	v_pk_add_f32 v[182:183], v[182:183], v[248:249]
	global_load_dwordx4 v[248:251], v[162:163], off offset:2048
	s_waitcnt vmcnt(1)
	v_pk_add_f32 v[180:181], v[180:181], v[154:155]
	v_pk_add_f32 v[182:183], v[182:183], v[152:153]
	global_load_dwordx4 v[152:155], v[236:237], off offset:2048
	s_waitcnt vmcnt(1)
	v_pk_add_f32 v[180:181], v[180:181], v[250:251]
	v_pk_add_f32 v[182:183], v[182:183], v[248:249]
	global_load_dwordx4 v[248:251], v[238:239], off offset:2048
	s_waitcnt vmcnt(1)
	v_pk_add_f32 v[180:181], v[180:181], v[154:155]
	v_pk_add_f32 v[182:183], v[182:183], v[152:153]
	global_load_dwordx4 v[152:155], v[240:241], off offset:2048
	s_waitcnt vmcnt(1)
	v_pk_add_f32 v[180:181], v[180:181], v[250:251]
	v_pk_add_f32 v[182:183], v[182:183], v[248:249]
	global_load_dwordx4 v[248:251], v[242:243], off offset:2048
	s_waitcnt vmcnt(1)
	v_pk_add_f32 v[180:181], v[180:181], v[154:155]
	v_pk_add_f32 v[182:183], v[182:183], v[152:153]
	global_load_dwordx4 v[152:155], v[230:231], off offset:-2048
	s_waitcnt vmcnt(1)
	v_pk_add_f32 v[180:181], v[180:181], v[250:251]
	v_pk_add_f32 v[182:183], v[182:183], v[248:249]
	global_load_dwordx4 v[248:251], v[156:157], off
	s_waitcnt vmcnt(1)
	v_pk_fma_f32 v[154:155], v[180:181], v[154:155], v[130:131]
	v_pk_fma_f32 v[152:153], v[182:183], v[152:153], v[128:129]
	global_load_dwordx4 v[156:159], v[158:159], off offset:3072
	s_waitcnt vmcnt(1)
	v_pk_add_f32 v[182:183], v[250:251], 0 op_sel_hi:[1,0]
	v_pk_add_f32 v[180:181], v[248:249], 0 op_sel_hi:[1,0]
	global_load_dwordx4 v[248:251], v[160:161], off offset:3072
	s_waitcnt vmcnt(1)
	v_pk_add_f32 v[182:183], v[182:183], v[158:159]
	v_pk_add_f32 v[180:181], v[180:181], v[156:157]
	global_load_dwordx4 v[156:159], v[162:163], off offset:3072
	s_waitcnt vmcnt(1)
	v_pk_add_f32 v[160:161], v[182:183], v[250:251]
	v_pk_add_f32 v[180:181], v[180:181], v[248:249]
	global_load_dwordx4 v[248:251], v[236:237], off offset:3072
	s_waitcnt vmcnt(1)
	v_pk_add_f32 v[160:161], v[160:161], v[158:159]
	v_pk_add_f32 v[162:163], v[180:181], v[156:157]
	global_load_dwordx4 v[156:159], v[238:239], off offset:3072
	s_waitcnt vmcnt(1)
	v_pk_add_f32 v[160:161], v[160:161], v[250:251]
	v_pk_add_f32 v[162:163], v[162:163], v[248:249]
	global_load_dwordx4 v[248:251], v[240:241], off offset:3072
	s_waitcnt vmcnt(1)
	v_pk_add_f32 v[160:161], v[160:161], v[158:159]
	v_pk_add_f32 v[162:163], v[162:163], v[156:157]
	global_load_dwordx4 v[156:159], v[242:243], off offset:3072
	s_waitcnt vmcnt(1)
	v_pk_add_f32 v[160:161], v[160:161], v[250:251]
	v_pk_add_f32 v[162:163], v[162:163], v[248:249]
	global_load_dwordx4 v[248:251], v[230:231], off offset:-1024
	s_waitcnt vmcnt(1)
	v_pk_add_f32 v[160:161], v[160:161], v[158:159]
	v_pk_add_f32 v[236:237], v[162:163], v[156:157]
	s_waitcnt vmcnt(0)
	v_pk_fma_f32 v[162:163], v[160:161], v[250:251], v[126:127]
	v_pk_fma_f32 v[160:161], v[236:237], v[248:249], v[124:125]
	v_add_co_u32_e32 v156, vcc, s1, v232
	v_ashrrev_i32_e32 v237, 31, v186
	s_nop 0
	v_addc_co_u32_e32 v157, vcc, -1, v233, vcc
	global_store_dwordx4 v[156:157], v[92:95], off offset:-3072
	global_store_dwordx4 v[156:157], v[132:135], off offset:-2048
	global_store_dwordx4 v[156:157], v[136:139], off offset:-1024
	global_store_dwordx4 v[232:233], v[140:143], off offset:-4096
	global_store_dwordx4 v[232:233], v[144:147], off offset:-3072
	global_store_dwordx4 v[232:233], v[148:151], off offset:-2048
	global_store_dwordx4 v[232:233], v[152:155], off offset:-1024
	global_store_dwordx4 v[232:233], v[160:163], off
	v_mov_b64_e32 v[156:157], v[160:161]
	v_mov_b32_e32 v236, v186
	v_mov_b64_e32 v[158:159], v[162:163]
	s_cbranch_execnz .LBB0_88
	s_branch .LBB0_95
